# code prefetch issued by one workgroup in four (8 per XCD) instead of every waiting workgroup
# speedup vs baseline: 1.0060x; 1.0060x over previous
_Z12trunk_kernel2KP:
	s_and_b32 s18, s2, 24
	s_cmp_lg_u32 s18, 0
	s_cbranch_scc1 .Lent_nopf
	s_getpc_b64 s[18:19]
	v_and_b32_e32 v254, 0x3ff, v0
	v_lshlrev_b32_e32 v254, 6, v254
	global_load_dword v255, v254, s[18:19]
.Lent_nopf:
	s_mov_b32 s88, s2
	s_load_dwordx2 s[80:81], s[0:1], 0x120
	s_load_dword s2, s[0:1], 0x12c
	s_load_dwordx2 s[86:87], s[0:1], 0x140
	s_mov_b64 s[92:93], s[0:1]
	s_add_u32 s6, s92, 0x140
	s_addc_u32 s7, s93, 0
	v_and_b32_e32 v174, 0x3ff, v0
	v_cmp_eq_u32_e64 s[8:9], 0, v174
	s_mov_b64 s[4:5], exec
	s_nop 0
	v_writelane_b32 v252, s8, 0
	s_nop 1
	v_writelane_b32 v252, s9, 1
	s_and_b64 s[8:9], s[4:5], s[8:9]
	s_mov_b64 exec, s[8:9]
	s_cbranch_execz .LBB0_2
	v_mov_b32_e32 v1, 0
	v_mov_b32_e32 v2, 0x20000
	ds_write_b32 v2, v1
	v_mov_b32_e32 v2, 0x20004
	ds_write_b32 v2, v1
	v_mov_b32_e32 v2, 0x20008
	ds_write_b32 v2, v1
	v_mov_b32_e32 v2, 0x2000c
	ds_write_b32 v2, v1

.Lxb_pf_0:
	v_readlane_b32 s18, v252, 5
	s_nop 3
	s_and_b32 s18, s18, 24
	s_cmp_lg_u32 s18, 0
	s_cbranch_scc1 .Lxb_wait_0
	s_getpc_b64 s[18:19]
	s_mov_b64 s[22:23], exec
	s_mov_b64 exec, -1
	v_mbcnt_lo_u32_b32 v254, -1, 0
	v_mbcnt_hi_u32_b32 v254, -1, v254
	v_lshlrev_b32_e32 v254, 7, v254
	global_load_dword v255, v254, s[18:19]
	s_add_u32 s18, s18, 0x2000
	s_addc_u32 s19, s19, 0
	global_load_dword v255, v254, s[18:19]
	s_add_u32 s18, s18, 0x2000
	s_addc_u32 s19, s19, 0
	global_load_dword v255, v254, s[18:19]
	s_add_u32 s18, s18, 0x2000
	s_addc_u32 s19, s19, 0
	global_load_dword v255, v254, s[18:19]
	s_mov_b64 exec, s[22:23]

.Lxb_pf_12:
	v_readlane_b32 s18, v252, 5
	s_nop 3
	s_and_b32 s18, s18, 24
	s_cmp_lg_u32 s18, 0
	s_cbranch_scc1 .Lxb_wait_12
	s_getpc_b64 s[18:19]
	s_mov_b64 s[22:23], exec
	s_mov_b64 exec, -1
	v_mbcnt_lo_u32_b32 v254, -1, 0
	v_mbcnt_hi_u32_b32 v254, -1, v254
	v_lshlrev_b32_e32 v254, 7, v254
	global_load_dword v255, v254, s[18:19]
	s_add_u32 s18, s18, 0x2000
	s_addc_u32 s19, s19, 0
	global_load_dword v255, v254, s[18:19]
	s_add_u32 s18, s18, 0x2000
	s_addc_u32 s19, s19, 0
	global_load_dword v255, v254, s[18:19]
	s_mov_b64 exec, s[22:23]

.Lxb_pf_13:
	v_readlane_b32 s18, v252, 5
	s_nop 3
	s_and_b32 s18, s18, 24
	s_cmp_lg_u32 s18, 0
	s_cbranch_scc1 .Lxb_wait_13
	s_getpc_b64 s[18:19]
	s_mov_b64 s[22:23], exec
	s_mov_b64 exec, -1
	v_mbcnt_lo_u32_b32 v254, -1, 0
	v_mbcnt_hi_u32_b32 v254, -1, v254
	v_lshlrev_b32_e32 v254, 7, v254
	global_load_dword v255, v254, s[18:19]
	s_mov_b64 exec, s[22:23]

.Lxb_pf_14:
	v_readlane_b32 s18, v252, 5
	s_nop 3
	s_and_b32 s18, s18, 24
	s_cmp_lg_u32 s18, 0
	s_cbranch_scc1 .Lxb_wait_14
	s_getpc_b64 s[18:19]
	s_mov_b64 s[22:23], exec
	s_mov_b64 exec, -1
	v_mbcnt_lo_u32_b32 v254, -1, 0
	v_mbcnt_hi_u32_b32 v254, -1, v254
	v_lshlrev_b32_e32 v254, 6, v254
	global_load_dword v255, v254, s[18:19]
	s_mov_b64 exec, s[22:23]
